# plus scalar-base addressing in the out-proj/FFN-down GEMM k-loop (with the readfirstlane wait-state fix)
# speedup vs baseline: 1.0134x; 1.0017x over previous
.Lgprio_3:
	v_lshl_add_u64 v[176:177], v[202:203], 1, v[192:193]
	s_nop 3
	v_readfirstlane_b32 s76, v176
	v_readfirstlane_b32 s77, v177
	s_sub_u32 s76, s76, 0x400000
	s_subb_u32 s77, s77, 0
	v_subrev_u32_e32 v202, s76, v176
	v_lshl_add_u64 v[176:177], v[204:205], 1, v[192:193]
	v_subrev_u32_e32 v204, s76, v176
	v_lshl_add_u64 v[176:177], v[206:207], 1, v[192:193]
	v_subrev_u32_e32 v206, s76, v176
	v_lshl_add_u64 v[176:177], v[208:209], 1, v[192:193]
	v_subrev_u32_e32 v208, s76, v176
	v_lshl_add_u64 v[176:177], v[210:211], 1, v[192:193]
	v_subrev_u32_e32 v210, s76, v176
	v_lshl_add_u64 v[176:177], v[212:213], 1, v[192:193]
	v_subrev_u32_e32 v212, s76, v176
	v_lshl_add_u64 v[176:177], v[214:215], 1, v[192:193]
	v_subrev_u32_e32 v214, s76, v176
	v_lshl_add_u64 v[176:177], v[216:217], 1, v[192:193]
	v_subrev_u32_e32 v216, s76, v176
	v_lshl_add_u64 v[176:177], v[218:219], 1, v[194:195]
	s_nop 3
	v_readfirstlane_b32 s78, v176
	v_readfirstlane_b32 s79, v177
	s_sub_u32 s78, s78, 0x400000
	s_subb_u32 s79, s79, 0
	v_subrev_u32_e32 v218, s78, v176
	v_lshl_add_u64 v[176:177], v[220:221], 1, v[194:195]
	v_subrev_u32_e32 v220, s78, v176
	v_lshl_add_u64 v[176:177], v[222:223], 1, v[194:195]
	v_subrev_u32_e32 v222, s78, v176
	v_lshl_add_u64 v[176:177], v[224:225], 1, v[194:195]
	v_subrev_u32_e32 v224, s78, v176
.LBB0_910:
	s_lshl_b64 s[8:9], s[50:51], 1
	s_waitcnt vmcnt(63) expcnt(7) lgkmcnt(15)
	s_barrier
	s_waitcnt vmcnt(0)
	ds_write_b128 v240, v[44:47]
	ds_write_b128 v240, v[40:43] offset:5120
	ds_write_b128 v240, v[36:39] offset:10240
	ds_write_b128 v240, v[32:35] offset:15360
	ds_write_b128 v240, v[28:31] offset:20480
	ds_write_b128 v240, v[24:27] offset:25600
	ds_write_b128 v240, v[20:23] offset:30720
	ds_write_b128 v240, v[16:19] offset:35840
	ds_write_b128 v240, v[12:15] offset:40960
	ds_write_b128 v240, v[8:11] offset:46080
	ds_write_b128 v240, v[4:7] offset:51200
	ds_write_b128 v240, v[0:3] offset:56320
	s_add_u32 s80, s76, s8
	s_addc_u32 s81, s77, s9
	s_add_u32 s82, s78, s8
	s_addc_u32 s83, s79, s9
	s_waitcnt lgkmcnt(0)
	s_barrier
	global_load_dwordx4 v[44:47], v202, s[80:81] sc1
	global_load_dwordx4 v[40:43], v204, s[80:81] sc1
	global_load_dwordx4 v[36:39], v206, s[80:81] sc1
	global_load_dwordx4 v[32:35], v208, s[80:81] sc1
	global_load_dwordx4 v[28:31], v210, s[80:81] sc1
	global_load_dwordx4 v[24:27], v212, s[80:81] sc1
	global_load_dwordx4 v[20:23], v214, s[80:81] sc1
	global_load_dwordx4 v[16:19], v216, s[80:81] sc1
	global_load_dwordx4 v[12:15], v218, s[82:83] sc1
	global_load_dwordx4 v[8:11], v220, s[82:83] sc1
	global_load_dwordx4 v[4:7], v222, s[82:83] sc1
	global_load_dwordx4 v[0:3], v224, s[82:83] sc1
	ds_read_b128 v[176:179], v241 offset:40960
	ds_read_b128 v[184:187], v241 offset:43520
	ds_read_b128 v[188:191], v241 offset:46080
	ds_read_b128 v[230:233], v241 offset:48640
	ds_read_b128 v[180:183], v239
	ds_read_b128 v[244:247], v239 offset:2560
	s_add_i32 s2, s2, -1
	s_add_i32 s50, s50, 64
	s_waitcnt lgkmcnt(1)
	v_mfma_f32_16x16x32_bf16 v[60:63], v[176:179], v[180:183], v[60:63]
	v_mfma_f32_16x16x32_bf16 v[64:67], v[184:187], v[180:183], v[64:67]
	v_mfma_f32_16x16x32_bf16 v[68:71], v[188:191], v[180:183], v[68:71]
	v_mfma_f32_16x16x32_bf16 v[76:79], v[230:233], v[180:183], v[76:79]
	ds_read_b128 v[180:183], v239 offset:5120
	s_waitcnt lgkmcnt(1)
	v_mfma_f32_16x16x32_bf16 v[72:75], v[176:179], v[244:247], v[72:75]
	v_mfma_f32_16x16x32_bf16 v[56:59], v[184:187], v[244:247], v[56:59]
	v_mfma_f32_16x16x32_bf16 v[52:55], v[188:191], v[244:247], v[52:55]
	v_mfma_f32_16x16x32_bf16 v[48:51], v[230:233], v[244:247], v[48:51]
	ds_read_b128 v[244:247], v239 offset:7680
	s_waitcnt lgkmcnt(1)
	v_mfma_f32_16x16x32_bf16 v[104:107], v[176:179], v[180:183], v[104:107]
	v_mfma_f32_16x16x32_bf16 v[92:95], v[184:187], v[180:183], v[92:95]
	v_mfma_f32_16x16x32_bf16 v[84:87], v[188:191], v[180:183], v[84:87]
	v_mfma_f32_16x16x32_bf16 v[80:83], v[230:233], v[180:183], v[80:83]
	ds_read_b128 v[180:183], v239 offset:10240
	s_waitcnt lgkmcnt(1)
	v_mfma_f32_16x16x32_bf16 v[120:123], v[176:179], v[244:247], v[120:123]
	v_mfma_f32_16x16x32_bf16 v[108:111], v[184:187], v[244:247], v[108:111]
	v_mfma_f32_16x16x32_bf16 v[96:99], v[188:191], v[244:247], v[96:99]
	v_mfma_f32_16x16x32_bf16 v[88:91], v[230:233], v[244:247], v[88:91]
	ds_read_b128 v[244:247], v239 offset:12800
	s_waitcnt lgkmcnt(1)
	v_mfma_f32_16x16x32_bf16 v[132:135], v[176:179], v[180:183], v[132:135]
	v_mfma_f32_16x16x32_bf16 v[124:127], v[184:187], v[180:183], v[124:127]
	v_mfma_f32_16x16x32_bf16 v[112:115], v[188:191], v[180:183], v[112:115]
	v_mfma_f32_16x16x32_bf16 v[100:103], v[230:233], v[180:183], v[100:103]
	ds_read_b128 v[180:183], v239 offset:15360
	s_waitcnt lgkmcnt(1)
	v_mfma_f32_16x16x32_bf16 v[140:143], v[176:179], v[244:247], v[140:143]
	v_mfma_f32_16x16x32_bf16 v[136:139], v[184:187], v[244:247], v[136:139]
	v_mfma_f32_16x16x32_bf16 v[128:131], v[188:191], v[244:247], v[128:131]
	v_mfma_f32_16x16x32_bf16 v[116:119], v[230:233], v[244:247], v[116:119]
	ds_read_b128 v[244:247], v242
	s_waitcnt lgkmcnt(1)
	v_mfma_f32_16x16x32_bf16 v[156:159], v[176:179], v[180:183], v[156:159]
	v_mfma_f32_16x16x32_bf16 v[152:155], v[184:187], v[180:183], v[152:155]
	v_mfma_f32_16x16x32_bf16 v[148:151], v[188:191], v[180:183], v[148:151]
	v_mfma_f32_16x16x32_bf16 v[144:147], v[230:233], v[180:183], v[144:147]
	ds_read_b128 v[180:183], v239 offset:64
	s_waitcnt lgkmcnt(1)
	v_mfma_f32_16x16x32_bf16 v[160:163], v[176:179], v[244:247], v[160:163]
	ds_read_b128 v[176:179], v241 offset:41024
	v_mfma_f32_16x16x32_bf16 v[164:167], v[184:187], v[244:247], v[164:167]
	ds_read_b128 v[184:187], v241 offset:43584
	v_mfma_f32_16x16x32_bf16 v[168:171], v[188:191], v[244:247], v[168:171]
	ds_read_b128 v[188:191], v241 offset:46144
	v_mfma_f32_16x16x32_bf16 v[172:175], v[230:233], v[244:247], v[172:175]
	ds_read_b128 v[230:233], v241 offset:48704
	ds_read_b128 v[244:247], v239 offset:2624
	s_waitcnt lgkmcnt(1)
	v_mfma_f32_16x16x32_bf16 v[60:63], v[176:179], v[180:183], v[60:63]
	v_mfma_f32_16x16x32_bf16 v[64:67], v[184:187], v[180:183], v[64:67]
	v_mfma_f32_16x16x32_bf16 v[68:71], v[188:191], v[180:183], v[68:71]
	v_mfma_f32_16x16x32_bf16 v[76:79], v[230:233], v[180:183], v[76:79]
	ds_read_b128 v[180:183], v239 offset:5184
	s_waitcnt lgkmcnt(1)
	v_mfma_f32_16x16x32_bf16 v[72:75], v[176:179], v[244:247], v[72:75]
	v_mfma_f32_16x16x32_bf16 v[56:59], v[184:187], v[244:247], v[56:59]
	v_mfma_f32_16x16x32_bf16 v[52:55], v[188:191], v[244:247], v[52:55]
	v_mfma_f32_16x16x32_bf16 v[48:51], v[230:233], v[244:247], v[48:51]
	ds_read_b128 v[244:247], v239 offset:7744
	s_waitcnt lgkmcnt(1)
	v_mfma_f32_16x16x32_bf16 v[104:107], v[176:179], v[180:183], v[104:107]
	v_mfma_f32_16x16x32_bf16 v[92:95], v[184:187], v[180:183], v[92:95]
	v_mfma_f32_16x16x32_bf16 v[84:87], v[188:191], v[180:183], v[84:87]
	v_mfma_f32_16x16x32_bf16 v[80:83], v[230:233], v[180:183], v[80:83]
	ds_read_b128 v[180:183], v239 offset:10304
	s_waitcnt lgkmcnt(1)
	v_mfma_f32_16x16x32_bf16 v[120:123], v[176:179], v[244:247], v[120:123]
	v_mfma_f32_16x16x32_bf16 v[108:111], v[184:187], v[244:247], v[108:111]
	v_mfma_f32_16x16x32_bf16 v[96:99], v[188:191], v[244:247], v[96:99]
	v_mfma_f32_16x16x32_bf16 v[88:91], v[230:233], v[244:247], v[88:91]
	ds_read_b128 v[244:247], v239 offset:12864
	s_waitcnt lgkmcnt(1)
	v_mfma_f32_16x16x32_bf16 v[132:135], v[176:179], v[180:183], v[132:135]
	v_mfma_f32_16x16x32_bf16 v[124:127], v[184:187], v[180:183], v[124:127]
	v_mfma_f32_16x16x32_bf16 v[112:115], v[188:191], v[180:183], v[112:115]
	v_mfma_f32_16x16x32_bf16 v[100:103], v[230:233], v[180:183], v[100:103]
	ds_read_b128 v[180:183], v239 offset:15424
	s_waitcnt lgkmcnt(1)
	v_mfma_f32_16x16x32_bf16 v[140:143], v[176:179], v[244:247], v[140:143]
	v_mfma_f32_16x16x32_bf16 v[136:139], v[184:187], v[244:247], v[136:139]
	v_mfma_f32_16x16x32_bf16 v[128:131], v[188:191], v[244:247], v[128:131]
	v_mfma_f32_16x16x32_bf16 v[116:119], v[230:233], v[244:247], v[116:119]
	ds_read_b128 v[244:247], v242 offset:64
	s_waitcnt lgkmcnt(1)
	v_mfma_f32_16x16x32_bf16 v[156:159], v[176:179], v[180:183], v[156:159]
	v_mfma_f32_16x16x32_bf16 v[152:155], v[184:187], v[180:183], v[152:155]
	v_mfma_f32_16x16x32_bf16 v[148:151], v[188:191], v[180:183], v[148:151]
	v_mfma_f32_16x16x32_bf16 v[144:147], v[230:233], v[180:183], v[144:147]
	s_waitcnt lgkmcnt(0)
	v_mfma_f32_16x16x32_bf16 v[160:163], v[176:179], v[244:247], v[160:163]
	v_mfma_f32_16x16x32_bf16 v[164:167], v[184:187], v[244:247], v[164:167]
	v_mfma_f32_16x16x32_bf16 v[168:171], v[188:191], v[244:247], v[168:171]
	v_mfma_f32_16x16x32_bf16 v[172:175], v[230:233], v[244:247], v[172:175]
	s_cmp_eq_u32 s2, 0
	s_cbranch_scc0 .LBB0_910
	s_setprio 0
	s_add_i32 s2, s15, 0xffffe000
	s_ashr_i32 s2, s2, 12
	s_mulk_i32 s2, 0x1800
	s_add_i32 s8, s2, 0x1800
	s_and_b64 s[2:3], s[18:19], exec
	s_cselect_b32 s8, 0, s8
	s_ashr_i32 s9, s8, 31
	s_barrier
	s_waitcnt vmcnt(11)
	ds_write_b128 v240, v[44:47]
	s_waitcnt vmcnt(10)
	ds_write_b128 v240, v[40:43] offset:5120
	s_waitcnt vmcnt(9)
	ds_write_b128 v240, v[36:39] offset:10240
	s_waitcnt vmcnt(8)
	ds_write_b128 v240, v[32:35] offset:15360
	s_waitcnt vmcnt(7)
	ds_write_b128 v240, v[28:31] offset:20480
	s_waitcnt vmcnt(6)
	ds_write_b128 v240, v[24:27] offset:25600
	s_waitcnt vmcnt(5)
	ds_write_b128 v240, v[20:23] offset:30720
	s_waitcnt vmcnt(4)
	ds_write_b128 v240, v[16:19] offset:35840
	s_waitcnt vmcnt(3)
	ds_write_b128 v240, v[12:15] offset:40960
	s_waitcnt vmcnt(2)
	ds_write_b128 v240, v[8:11] offset:46080
	s_waitcnt vmcnt(1)
	ds_write_b128 v240, v[4:7] offset:51200
	s_waitcnt vmcnt(0)
	ds_write_b128 v240, v[0:3] offset:56320
	s_waitcnt lgkmcnt(0)
	s_barrier
	ds_read_b128 v[0:3], v241 offset:40960
	ds_read_b128 v[4:7], v241 offset:43520
	ds_read_b128 v[8:11], v241 offset:46080
	ds_read_b128 v[12:15], v241 offset:48640
	ds_read_b128 v[16:19], v239 offset:2560
	ds_read_b128 v[20:23], v239 offset:5120
	ds_read_b128 v[24:27], v239
	ds_read_b128 v[40:43], v239 offset:7680
	s_lshl_b64 s[2:3], s[8:9], 2
	s_waitcnt lgkmcnt(3)
	v_mfma_f32_16x16x32_bf16 v[44:47], v[0:3], v[16:19], v[72:75]
	s_add_u32 s2, s11, s2
	s_addc_u32 s3, s12, s3
	v_mov_b32_e32 v201, v197
	s_waitcnt lgkmcnt(1)
	v_mfma_f32_16x16x32_bf16 v[28:31], v[0:3], v[24:27], v[60:63]
	ds_read_b128 v[72:75], v239 offset:12800
	s_add_i32 s14, s14, s53
	s_cmp_gt_u32 s14, 63
	v_mfma_f32_16x16x32_bf16 v[32:35], v[4:7], v[24:27], v[64:67]
	v_mfma_f32_16x16x32_bf16 v[36:39], v[8:11], v[24:27], v[68:71]
	v_mfma_f32_16x16x32_bf16 v[24:27], v[12:15], v[24:27], v[76:79]
	v_mfma_f32_16x16x32_bf16 v[56:59], v[4:7], v[16:19], v[56:59]
	v_mfma_f32_16x16x32_bf16 v[52:55], v[8:11], v[16:19], v[52:55]
	v_mfma_f32_16x16x32_bf16 v[16:19], v[12:15], v[16:19], v[48:51]
	s_nop 2
	ds_read_b128 v[48:51], v239 offset:10240
	v_mfma_f32_16x16x32_bf16 v[60:63], v[0:3], v[20:23], v[104:107]
	v_mfma_f32_16x16x32_bf16 v[64:67], v[4:7], v[20:23], v[92:95]
	v_mfma_f32_16x16x32_bf16 v[68:71], v[8:11], v[20:23], v[84:87]
	s_nop 1
	ds_read_b128 v[92:95], v242
	v_mfma_f32_16x16x32_bf16 v[20:23], v[12:15], v[20:23], v[80:83]
	s_waitcnt lgkmcnt(3)
	v_mfma_f32_16x16x32_bf16 v[76:79], v[0:3], v[40:43], v[120:123]
	v_mfma_f32_16x16x32_bf16 v[80:83], v[4:7], v[40:43], v[108:111]
	v_mfma_f32_16x16x32_bf16 v[84:87], v[8:11], v[40:43], v[96:99]
	v_mfma_f32_16x16x32_bf16 v[40:43], v[12:15], v[40:43], v[88:91]
	s_nop 2
	ds_read_b128 v[88:91], v239 offset:15360
	s_waitcnt lgkmcnt(2)
	v_mfma_f32_16x16x32_bf16 v[176:179], v[0:3], v[48:51], v[132:135]
	v_mfma_f32_16x16x32_bf16 v[180:183], v[4:7], v[48:51], v[124:127]
	v_mfma_f32_16x16x32_bf16 v[184:187], v[8:11], v[48:51], v[112:115]
	v_mfma_f32_16x16x32_bf16 v[48:51], v[12:15], v[48:51], v[100:103]
	v_mfma_f32_16x16x32_bf16 v[188:191], v[0:3], v[72:75], v[140:143]
	v_mfma_f32_16x16x32_bf16 v[202:205], v[4:7], v[72:75], v[136:139]
	v_mfma_f32_16x16x32_bf16 v[206:209], v[8:11], v[72:75], v[128:131]
	v_mfma_f32_16x16x32_bf16 v[210:213], v[12:15], v[72:75], v[116:119]
	s_waitcnt lgkmcnt(0)
	v_mfma_f32_16x16x32_bf16 v[156:159], v[0:3], v[88:91], v[156:159]
	v_mfma_f32_16x16x32_bf16 v[152:155], v[4:7], v[88:91], v[152:155]
	v_mfma_f32_16x16x32_bf16 v[148:151], v[8:11], v[88:91], v[148:151]
	v_mfma_f32_16x16x32_bf16 v[144:147], v[12:15], v[88:91], v[144:147]
	v_mfma_f32_16x16x32_bf16 v[0:3], v[0:3], v[92:95], v[160:163]
	v_mfma_f32_16x16x32_bf16 v[4:7], v[4:7], v[92:95], v[164:167]
	v_mfma_f32_16x16x32_bf16 v[8:11], v[8:11], v[92:95], v[168:171]
	v_mfma_f32_16x16x32_bf16 v[160:163], v[12:15], v[92:95], v[172:175]
	ds_read_b128 v[12:15], v241 offset:41024
	ds_read_b128 v[164:167], v241 offset:43584
	ds_read_b128 v[168:171], v241 offset:46144
	ds_read_b128 v[172:175], v241 offset:48704
	ds_read_b128 v[72:75], v239 offset:2624
	ds_read_b128 v[88:91], v239 offset:5184
	ds_read_b128 v[92:95], v239 offset:64
	s_waitcnt lgkmcnt(0)
	v_mfma_f32_16x16x32_bf16 v[128:131], v[172:175], v[92:95], v[24:27]
	s_nop 2
	ds_read_b128 v[24:27], v239 offset:7744
	v_mfma_f32_16x16x32_bf16 v[116:119], v[168:171], v[72:75], v[52:55]
	v_mfma_f32_16x16x32_bf16 v[112:115], v[172:175], v[72:75], v[16:19]
	s_nop 1
	ds_read_b128 v[52:55], v239 offset:15424
	ds_read_b128 v[16:19], v239 offset:10304
	v_mfma_f32_16x16x32_bf16 v[108:111], v[12:15], v[88:91], v[60:63]
	v_mfma_f32_16x16x32_bf16 v[96:99], v[172:175], v[88:91], v[20:23]
	s_nop 1
	ds_read_b128 v[60:63], v242 offset:64
	ds_read_b128 v[20:23], v239 offset:12864
	v_mfma_f32_16x16x32_bf16 v[140:143], v[12:15], v[92:95], v[28:31]
	v_mfma_f32_16x16x32_bf16 v[136:139], v[164:167], v[92:95], v[32:35]
	v_mfma_f32_16x16x32_bf16 v[132:135], v[168:171], v[92:95], v[36:39]
	v_mfma_f32_16x16x32_bf16 v[124:127], v[12:15], v[72:75], v[44:47]
	v_mfma_f32_16x16x32_bf16 v[120:123], v[164:167], v[72:75], v[56:59]
	v_mfma_f32_16x16x32_bf16 v[104:107], v[164:167], v[88:91], v[64:67]
	v_mfma_f32_16x16x32_bf16 v[100:103], v[168:171], v[88:91], v[68:71]
	s_waitcnt lgkmcnt(4)
	v_mfma_f32_16x16x32_bf16 v[92:95], v[12:15], v[24:27], v[76:79]
	v_mfma_f32_16x16x32_bf16 v[88:91], v[164:167], v[24:27], v[80:83]
	v_mfma_f32_16x16x32_bf16 v[80:83], v[172:175], v[24:27], v[40:43]
	s_waitcnt lgkmcnt(2)
	v_mfma_f32_16x16x32_bf16 v[76:79], v[12:15], v[16:19], v[176:179]
	v_mfma_f32_16x16x32_bf16 v[72:75], v[164:167], v[16:19], v[180:183]
	v_mfma_f32_16x16x32_bf16 v[64:67], v[168:171], v[16:19], v[184:187]
	v_mfma_f32_16x16x32_bf16 v[56:59], v[172:175], v[16:19], v[48:51]
	s_waitcnt lgkmcnt(0)
	v_mfma_f32_16x16x32_bf16 v[48:51], v[12:15], v[20:23], v[188:191]
	v_mfma_f32_16x16x32_bf16 v[44:47], v[164:167], v[20:23], v[202:205]
	v_mfma_f32_16x16x32_bf16 v[40:43], v[168:171], v[20:23], v[206:209]
	v_mfma_f32_16x16x32_bf16 v[36:39], v[172:175], v[20:23], v[210:213]
	v_mfma_f32_16x16x32_bf16 v[32:35], v[12:15], v[52:55], v[156:159]
	v_mfma_f32_16x16x32_bf16 v[20:23], v[172:175], v[52:55], v[144:147]
	v_mfma_f32_16x16x32_bf16 v[16:19], v[12:15], v[60:63], v[0:3]
	s_nop 1
	v_add_u32_e32 v146, s15, v238
	v_ashrrev_i32_e32 v147, 31, v146
	v_mfma_f32_16x16x32_bf16 v[12:15], v[164:167], v[60:63], v[4:7]
	s_nop 2
	v_or_b32_e32 v4, s16, v226
	v_lshlrev_b32_e32 v196, 2, v4
	v_mfma_f32_16x16x32_bf16 v[84:87], v[168:171], v[24:27], v[84:87]
	v_lshl_add_u64 v[4:5], s[2:3], 0, v[196:197]
	v_lshl_add_u64 v[144:145], v[198:199], 0, v[196:197]
	v_lshl_add_u64 v[4:5], v[4:5], 0, v[200:201]
	v_mfma_f32_16x16x32_bf16 v[24:27], v[168:171], v[52:55], v[148:151]
	s_nop 2
	v_lshlrev_b64 v[148:149], 12, v[146:147]
	v_mfma_f32_16x16x32_bf16 v[28:31], v[164:167], v[52:55], v[152:155]
	s_nop 2
	v_lshl_add_u64 v[152:153], v[144:145], 0, v[148:149]
	v_mfma_f32_16x16x32_bf16 v[8:11], v[168:171], v[60:63], v[8:11]
	v_mfma_f32_16x16x32_bf16 v[0:3], v[172:175], v[60:63], v[160:163]
	global_load_dwordx4 v[68:71], v[4:5], off sc1
	global_load_dwordx4 v[60:63], v[4:5], off offset:64 sc1
	global_load_dwordx4 v[52:55], v[4:5], off offset:128 sc1
	s_nop 0
	global_load_dwordx4 v[4:7], v[4:5], off offset:192 sc1
	s_nop 0
	global_load_dwordx4 v[148:151], v[152:153], off sc1
	s_waitcnt vmcnt(0)
	v_pk_fma_f32 v[142:143], v[142:143], v[70:71], v[150:151]
	v_pk_fma_f32 v[140:141], v[140:141], v[68:69], v[148:149]
	global_store_dwordx4 v[152:153], v[140:143], off
	global_load_dwordx4 v[140:143], v[152:153], off offset:64 sc1
	s_waitcnt vmcnt(0)
	v_pk_fma_f32 v[138:139], v[138:139], v[62:63], v[142:143]
	v_pk_fma_f32 v[136:137], v[136:137], v[60:61], v[140:141]
	global_store_dwordx4 v[152:153], v[136:139], off offset:64
	global_load_dwordx4 v[136:139], v[152:153], off offset:128 sc1
	s_waitcnt vmcnt(0)
	v_pk_fma_f32 v[134:135], v[134:135], v[54:55], v[138:139]
	v_pk_fma_f32 v[132:133], v[132:133], v[52:53], v[136:137]
	global_store_dwordx4 v[152:153], v[132:135], off offset:128
	global_load_dwordx4 v[132:135], v[152:153], off offset:192 sc1
	s_waitcnt vmcnt(0)
	v_pk_fma_f32 v[130:131], v[130:131], v[6:7], v[134:135]
	v_pk_fma_f32 v[128:129], v[128:129], v[4:5], v[132:133]
	global_store_dwordx4 v[152:153], v[128:131], off offset:192
	s_nop 1
	v_or_b32_e32 v128, 16, v146
	v_ashrrev_i32_e32 v129, 31, v128
	v_lshlrev_b64 v[128:129], 12, v[128:129]
	v_lshl_add_u64 v[132:133], v[144:145], 0, v[128:129]
	global_load_dwordx4 v[128:131], v[132:133], off sc1
	s_waitcnt vmcnt(0)
	v_pk_fma_f32 v[126:127], v[126:127], v[70:71], v[130:131]
	v_pk_fma_f32 v[124:125], v[124:125], v[68:69], v[128:129]
	global_store_dwordx4 v[132:133], v[124:127], off
	global_load_dwordx4 v[124:127], v[132:133], off offset:64 sc1
	s_waitcnt vmcnt(0)
	v_pk_fma_f32 v[122:123], v[122:123], v[62:63], v[126:127]
	v_pk_fma_f32 v[120:121], v[120:121], v[60:61], v[124:125]
	global_store_dwordx4 v[132:133], v[120:123], off offset:64
	global_load_dwordx4 v[120:123], v[132:133], off offset:128 sc1
	s_waitcnt vmcnt(0)
	v_pk_fma_f32 v[118:119], v[118:119], v[54:55], v[122:123]
	v_pk_fma_f32 v[116:117], v[116:117], v[52:53], v[120:121]
	global_store_dwordx4 v[132:133], v[116:119], off offset:128
	global_load_dwordx4 v[116:119], v[132:133], off offset:192 sc1
	s_waitcnt vmcnt(0)
	v_pk_fma_f32 v[114:115], v[114:115], v[6:7], v[118:119]
	v_pk_fma_f32 v[112:113], v[112:113], v[4:5], v[116:117]
	global_store_dwordx4 v[132:133], v[112:115], off offset:192
	s_nop 1
	v_or_b32_e32 v112, 32, v146
	v_ashrrev_i32_e32 v113, 31, v112
	v_lshlrev_b64 v[112:113], 12, v[112:113]
	v_lshl_add_u64 v[116:117], v[144:145], 0, v[112:113]
	global_load_dwordx4 v[112:115], v[116:117], off sc1
	s_waitcnt vmcnt(0)
	v_pk_fma_f32 v[110:111], v[110:111], v[70:71], v[114:115]
	v_pk_fma_f32 v[108:109], v[108:109], v[68:69], v[112:113]
	global_store_dwordx4 v[116:117], v[108:111], off
	global_load_dwordx4 v[108:111], v[116:117], off offset:64 sc1
	s_waitcnt vmcnt(0)
	v_pk_fma_f32 v[106:107], v[106:107], v[62:63], v[110:111]
	v_pk_fma_f32 v[104:105], v[104:105], v[60:61], v[108:109]
	global_store_dwordx4 v[116:117], v[104:107], off offset:64
	global_load_dwordx4 v[104:107], v[116:117], off offset:128 sc1
	s_waitcnt vmcnt(0)
	v_pk_fma_f32 v[102:103], v[102:103], v[54:55], v[106:107]
	v_pk_fma_f32 v[100:101], v[100:101], v[52:53], v[104:105]
	global_store_dwordx4 v[116:117], v[100:103], off offset:128
	global_load_dwordx4 v[100:103], v[116:117], off offset:192 sc1
	s_waitcnt vmcnt(0)
	v_pk_fma_f32 v[98:99], v[98:99], v[6:7], v[102:103]
	v_pk_fma_f32 v[96:97], v[96:97], v[4:5], v[100:101]
	global_store_dwordx4 v[116:117], v[96:99], off offset:192
	s_nop 1
	v_or_b32_e32 v96, 48, v146
	v_ashrrev_i32_e32 v97, 31, v96
	v_lshlrev_b64 v[96:97], 12, v[96:97]
	v_lshl_add_u64 v[100:101], v[144:145], 0, v[96:97]
	global_load_dwordx4 v[96:99], v[100:101], off sc1
	s_waitcnt vmcnt(0)
	v_pk_fma_f32 v[94:95], v[94:95], v[70:71], v[98:99]
	v_pk_fma_f32 v[92:93], v[92:93], v[68:69], v[96:97]
	global_store_dwordx4 v[100:101], v[92:95], off
	global_load_dwordx4 v[92:95], v[100:101], off offset:64 sc1
	s_waitcnt vmcnt(0)
	v_pk_fma_f32 v[90:91], v[90:91], v[62:63], v[94:95]
	v_pk_fma_f32 v[88:89], v[88:89], v[60:61], v[92:93]
	global_store_dwordx4 v[100:101], v[88:91], off offset:64
	global_load_dwordx4 v[88:91], v[100:101], off offset:128 sc1
	s_waitcnt vmcnt(0)
	v_pk_fma_f32 v[86:87], v[86:87], v[54:55], v[90:91]
	v_pk_fma_f32 v[84:85], v[84:85], v[52:53], v[88:89]
	global_store_dwordx4 v[100:101], v[84:87], off offset:128
	global_load_dwordx4 v[84:87], v[100:101], off offset:192 sc1
	s_waitcnt vmcnt(0)
	v_pk_fma_f32 v[82:83], v[82:83], v[6:7], v[86:87]
	v_pk_fma_f32 v[80:81], v[80:81], v[4:5], v[84:85]
	global_store_dwordx4 v[100:101], v[80:83], off offset:192
	s_nop 1
	v_or_b32_e32 v80, 64, v146
	v_ashrrev_i32_e32 v81, 31, v80
	v_lshlrev_b64 v[80:81], 12, v[80:81]
	v_lshl_add_u64 v[84:85], v[144:145], 0, v[80:81]
	global_load_dwordx4 v[80:83], v[84:85], off sc1
	s_waitcnt vmcnt(0)
	v_pk_fma_f32 v[78:79], v[78:79], v[70:71], v[82:83]
	v_pk_fma_f32 v[76:77], v[76:77], v[68:69], v[80:81]
	global_store_dwordx4 v[84:85], v[76:79], off
	global_load_dwordx4 v[76:79], v[84:85], off offset:64 sc1
	s_waitcnt vmcnt(0)
	v_pk_fma_f32 v[74:75], v[74:75], v[62:63], v[78:79]
	v_pk_fma_f32 v[72:73], v[72:73], v[60:61], v[76:77]
	global_store_dwordx4 v[84:85], v[72:75], off offset:64
	global_load_dwordx4 v[72:75], v[84:85], off offset:128 sc1
	s_waitcnt vmcnt(0)
	v_pk_fma_f32 v[66:67], v[66:67], v[54:55], v[74:75]
	v_pk_fma_f32 v[64:65], v[64:65], v[52:53], v[72:73]
	global_store_dwordx4 v[84:85], v[64:67], off offset:128
	global_load_dwordx4 v[64:67], v[84:85], off offset:192 sc1
	s_waitcnt vmcnt(0)
	v_pk_fma_f32 v[58:59], v[58:59], v[6:7], v[66:67]
	v_pk_fma_f32 v[56:57], v[56:57], v[4:5], v[64:65]
	global_store_dwordx4 v[84:85], v[56:59], off offset:192
	s_nop 1
	v_or_b32_e32 v56, 0x50, v146
	v_ashrrev_i32_e32 v57, 31, v56
	v_lshlrev_b64 v[56:57], 12, v[56:57]
	v_lshl_add_u64 v[64:65], v[144:145], 0, v[56:57]
	global_load_dwordx4 v[56:59], v[64:65], off sc1
	s_waitcnt vmcnt(0)
	v_pk_fma_f32 v[50:51], v[50:51], v[70:71], v[58:59]
	v_pk_fma_f32 v[48:49], v[48:49], v[68:69], v[56:57]
	global_store_dwordx4 v[64:65], v[48:51], off
	global_load_dwordx4 v[48:51], v[64:65], off offset:64 sc1
	s_waitcnt vmcnt(0)
	v_pk_fma_f32 v[46:47], v[46:47], v[62:63], v[50:51]
	v_pk_fma_f32 v[44:45], v[44:45], v[60:61], v[48:49]
	global_store_dwordx4 v[64:65], v[44:47], off offset:64
	global_load_dwordx4 v[44:47], v[64:65], off offset:128 sc1
	s_waitcnt vmcnt(0)
	v_pk_fma_f32 v[42:43], v[42:43], v[54:55], v[46:47]
	v_pk_fma_f32 v[40:41], v[40:41], v[52:53], v[44:45]
	global_store_dwordx4 v[64:65], v[40:43], off offset:128
	global_load_dwordx4 v[40:43], v[64:65], off offset:192 sc1
	s_waitcnt vmcnt(0)
	v_pk_fma_f32 v[38:39], v[38:39], v[6:7], v[42:43]
	v_pk_fma_f32 v[36:37], v[36:37], v[4:5], v[40:41]
	global_store_dwordx4 v[64:65], v[36:39], off offset:192
	s_nop 1
	v_or_b32_e32 v36, 0x60, v146
	v_ashrrev_i32_e32 v37, 31, v36
	v_lshlrev_b64 v[36:37], 12, v[36:37]
	v_lshl_add_u64 v[40:41], v[144:145], 0, v[36:37]
	global_load_dwordx4 v[36:39], v[40:41], off sc1
	s_waitcnt vmcnt(0)
	v_pk_fma_f32 v[34:35], v[34:35], v[70:71], v[38:39]
	v_pk_fma_f32 v[32:33], v[32:33], v[68:69], v[36:37]
	global_store_dwordx4 v[40:41], v[32:35], off
	global_load_dwordx4 v[32:35], v[40:41], off offset:64 sc1
	s_waitcnt vmcnt(0)
	v_pk_fma_f32 v[30:31], v[30:31], v[62:63], v[34:35]
	v_pk_fma_f32 v[28:29], v[28:29], v[60:61], v[32:33]
	global_store_dwordx4 v[40:41], v[28:31], off offset:64
	global_load_dwordx4 v[28:31], v[40:41], off offset:128 sc1
	s_waitcnt vmcnt(0)
	v_pk_fma_f32 v[26:27], v[26:27], v[54:55], v[30:31]
	v_pk_fma_f32 v[24:25], v[24:25], v[52:53], v[28:29]
	global_store_dwordx4 v[40:41], v[24:27], off offset:128
	global_load_dwordx4 v[24:27], v[40:41], off offset:192 sc1
	s_waitcnt vmcnt(0)
	v_pk_fma_f32 v[22:23], v[22:23], v[6:7], v[26:27]
	v_pk_fma_f32 v[20:21], v[20:21], v[4:5], v[24:25]
	global_store_dwordx4 v[40:41], v[20:23], off offset:192
	s_nop 1
	v_or_b32_e32 v20, 0x70, v146
	v_ashrrev_i32_e32 v21, 31, v20
	v_lshlrev_b64 v[20:21], 12, v[20:21]
	v_lshl_add_u64 v[20:21], v[144:145], 0, v[20:21]
	global_load_dwordx4 v[22:25], v[20:21], off sc1
	s_waitcnt vmcnt(0)
	v_pk_fma_f32 v[18:19], v[18:19], v[70:71], v[24:25]
	v_pk_fma_f32 v[16:17], v[16:17], v[68:69], v[22:23]
	global_store_dwordx4 v[20:21], v[16:19], off
	global_load_dwordx4 v[16:19], v[20:21], off offset:64 sc1
	s_waitcnt vmcnt(0)
	v_pk_fma_f32 v[14:15], v[14:15], v[62:63], v[18:19]
	v_pk_fma_f32 v[12:13], v[12:13], v[60:61], v[16:17]
	global_store_dwordx4 v[20:21], v[12:15], off offset:64
	global_load_dwordx4 v[12:15], v[20:21], off offset:128 sc1
	s_waitcnt vmcnt(0)
	v_pk_fma_f32 v[10:11], v[10:11], v[54:55], v[14:15]
	v_pk_fma_f32 v[8:9], v[8:9], v[52:53], v[12:13]
	global_store_dwordx4 v[20:21], v[8:11], off offset:128
	global_load_dwordx4 v[8:11], v[20:21], off offset:192 sc1
	s_waitcnt vmcnt(0)
	v_pk_fma_f32 v[2:3], v[2:3], v[6:7], v[10:11]
	v_pk_fma_f32 v[0:1], v[0:1], v[4:5], v[8:9]
	global_store_dwordx4 v[20:21], v[0:3], off offset:192
	s_cbranch_scc0 .LBB0_909
